# grid barriers: flat release (all WGs poll the top counter), L1 invalidate issued before polling, leader inv overlapped with L2 write-back
# speedup vs baseline: 1.3091x; 1.0075x over previous
.LBB0_61:
	v_mov_b32_e32 v0, 0x25fc0
	s_waitcnt vmcnt(0) lgkmcnt(0)
	ds_read_b64 v[2:3], v0
	v_readlane_b32 s3, v233, 8
	v_mov_b32_e32 v1, 1
	s_lshl_b32 s3, s3, 8
	s_add_i32 s3, s3, 0x5400
	v_mov_b32_e32 v0, s3
	global_atomic_add v4, v0, v1, s[48:49] sc0
	s_waitcnt vmcnt(0) lgkmcnt(0)
	v_readfirstlane_b32 s4, v4
	v_readfirstlane_b32 s5, v2
	v_readfirstlane_b32 s16, v3
	s_nop 3
	s_mov_b32 s17, s5
	s_mov_b32 s3, s16
.Lxb0_gen:
	s_cmp_lt_u32 s4, s17
	s_cbranch_scc1 .Lxb0_gend
	s_add_u32 s17, s17, s5
	s_add_u32 s3, s3, s16
	s_branch .Lxb0_gen
.Lxb0_gend:
	s_add_u32 s4, s4, 1
	v_mov_b32_e32 v0, 0x7400
	s_cmp_lg_u32 s4, s17
	s_cbranch_scc1 .Lxb0_nl
	buffer_wbl2 sc1
	buffer_inv sc1
	s_waitcnt vmcnt(0)
	global_atomic_add v0, v1, s[48:49]
	s_branch .Lxb0_poll

.Lxb0_poll:
	s_mov_b32 s5, 0
.Lxb0_spin:
	global_load_dword v4, v0, s[48:49] sc1
	s_waitcnt vmcnt(0)
	v_readfirstlane_b32 s4, v4
	s_add_u32 s5, s5, 1
	s_nop 3
	s_cmp_ge_u32 s4, s3
	s_cbranch_scc1 .Lxb0_done
	s_sleep 1
	s_cmp_lt_u32 s5, 0x40000
	s_cbranch_scc1 .Lxb0_spin
.Lxb0_done:
.LBB0_97:
	s_or_b64 exec, exec, s[8:9]
	s_waitcnt lgkmcnt(0)
	s_barrier

.LBB0_145:
	v_readlane_b32 s4, v233, 2
	v_readlane_b32 s5, v233, 3
	v_readlane_b32 s6, v233, 4
	v_readlane_b32 s7, v233, 5
	s_cmp_gt_i32 s5, 2
	s_cselect_b64 s[6:7], -1, 0
	s_and_b64 s[4:5], s[8:9], s[6:7]
	s_andn2_b64 vcc, exec, s[4:5]
	s_cbranch_vccnz .LBB0_199
	s_waitcnt vmcnt(0)
	v_readlane_b32 s0, v233, 9
	v_readlane_b32 s1, v233, 10
	s_waitcnt vmcnt(0)
	s_barrier
	s_and_saveexec_b64 s[8:9], s[0:1]
	s_cbranch_execz .LBB0_198
	v_mov_b32_e32 v0, 0x25fc0
	s_waitcnt vmcnt(0) lgkmcnt(0)
	ds_read_b64 v[2:3], v0
	v_readlane_b32 s3, v233, 8
	v_mov_b32_e32 v1, 1
	s_lshl_b32 s3, s3, 8
	s_add_i32 s3, s3, 0x5400
	v_mov_b32_e32 v0, s3
	global_atomic_add v4, v0, v1, s[48:49] sc0
	s_waitcnt vmcnt(0) lgkmcnt(0)
	v_readfirstlane_b32 s4, v4
	v_readfirstlane_b32 s5, v2
	v_readfirstlane_b32 s16, v3
	s_nop 3
	s_mov_b32 s17, s5
	s_mov_b32 s3, s16

.LBB0_689:
	v_readlane_b32 s4, v233, 2
	v_readlane_b32 s5, v233, 3
	v_readlane_b32 s6, v233, 4
	v_readlane_b32 s7, v233, 5
	s_cmp_gt_i32 s5, 4
	v_readlane_b32 s0, v233, 34
	s_cselect_b64 s[6:7], -1, 0
	v_readlane_b32 s1, v233, 35
	s_and_b64 s[4:5], s[0:1], s[6:7]
	s_andn2_b64 vcc, exec, s[4:5]
	v_readlane_b32 s12, v233, 33
	s_cbranch_vccnz .LBB0_743
	s_waitcnt vmcnt(0)
	v_readlane_b32 s0, v233, 9
	v_readlane_b32 s1, v233, 10
	s_waitcnt vmcnt(0)
	s_barrier
	s_and_saveexec_b64 s[8:9], s[0:1]
	s_cbranch_execz .LBB0_742
	v_mov_b32_e32 v0, 0x25fc0
	s_waitcnt vmcnt(0) lgkmcnt(0)
	ds_read_b64 v[2:3], v0
	v_readlane_b32 s3, v233, 8
	v_mov_b32_e32 v1, 1
	s_lshl_b32 s3, s3, 8
	s_add_i32 s3, s3, 0x5400
	v_mov_b32_e32 v0, s3
	global_atomic_add v4, v0, v1, s[48:49] sc0
	s_waitcnt vmcnt(0) lgkmcnt(0)
	v_readfirstlane_b32 s4, v4
	v_readfirstlane_b32 s5, v2
	v_readfirstlane_b32 s16, v3
	s_nop 3
	s_mov_b32 s17, s5
	s_mov_b32 s3, s16

.LBB0_850:
	v_readlane_b32 s4, v233, 2
	v_readlane_b32 s5, v233, 3
	v_readlane_b32 s6, v233, 4
	v_readlane_b32 s7, v233, 5
	s_cmp_gt_i32 s5, 5
	s_cselect_b64 s[6:7], -1, 0
	s_and_b64 s[4:5], s[16:17], s[6:7]
	s_andn2_b64 vcc, exec, s[4:5]
	s_cbranch_vccnz .LBB0_904
	s_waitcnt vmcnt(0)
	v_readlane_b32 s0, v233, 9
	v_readlane_b32 s1, v233, 10
	s_waitcnt vmcnt(0) lgkmcnt(0)
	s_barrier
	s_and_saveexec_b64 s[8:9], s[0:1]
	s_cbranch_execz .LBB0_903
	v_mov_b32_e32 v0, 0x25fc0
	s_waitcnt vmcnt(0) lgkmcnt(0)
	ds_read_b64 v[2:3], v0
	v_readlane_b32 s3, v233, 8
	v_mov_b32_e32 v1, 1
	s_lshl_b32 s3, s3, 8
	s_add_i32 s3, s3, 0x5400
	v_mov_b32_e32 v0, s3
	global_atomic_add v4, v0, v1, s[48:49] sc0
	s_waitcnt vmcnt(0) lgkmcnt(0)
	v_readfirstlane_b32 s4, v4
	v_readfirstlane_b32 s5, v2
	v_readfirstlane_b32 s16, v3
	s_nop 3
	s_mov_b32 s17, s5
	s_mov_b32 s3, s16

.LBB0_943:
	v_readlane_b32 s4, v233, 2
	v_readlane_b32 s5, v233, 3
	v_readlane_b32 s6, v233, 4
	v_readlane_b32 s7, v233, 5
	s_cmp_gt_i32 s5, 6
	s_cselect_b64 s[6:7], -1, 0
	s_and_b64 s[4:5], s[26:27], s[6:7]
	s_andn2_b64 vcc, exec, s[4:5]
	s_cbranch_vccnz .LBB0_997
	s_waitcnt vmcnt(0)
	v_readlane_b32 s0, v233, 9
	v_readlane_b32 s1, v233, 10
	s_waitcnt vmcnt(0) lgkmcnt(0)
	s_barrier
	s_and_saveexec_b64 s[8:9], s[0:1]
	s_cbranch_execz .LBB0_996
	v_mov_b32_e32 v0, 0x25fc0
	s_waitcnt vmcnt(0) lgkmcnt(0)
	ds_read_b64 v[2:3], v0
	v_readlane_b32 s3, v233, 8
	v_mov_b32_e32 v1, 1
	s_lshl_b32 s3, s3, 8
	s_add_i32 s3, s3, 0x5400
	v_mov_b32_e32 v0, s3
	global_atomic_add v4, v0, v1, s[48:49] sc0
	s_waitcnt vmcnt(0) lgkmcnt(0)
	v_readfirstlane_b32 s4, v4
	v_readfirstlane_b32 s5, v2
	v_readfirstlane_b32 s16, v3
	s_nop 3
	s_mov_b32 s17, s5
	s_mov_b32 s3, s16

.LBB0_1008:
	v_readlane_b32 s4, v233, 2
	v_readlane_b32 s5, v233, 3
	v_readlane_b32 s6, v233, 4
	v_readlane_b32 s7, v233, 5
	s_cmp_gt_i32 s5, 7
	s_cselect_b64 s[6:7], -1, 0
	s_and_b64 s[4:5], s[8:9], s[6:7]
	s_andn2_b64 vcc, exec, s[4:5]
	s_cbranch_vccnz .LBB0_1062
	s_waitcnt vmcnt(0)
	v_readlane_b32 s0, v233, 9
	v_readlane_b32 s1, v233, 10
	s_waitcnt vmcnt(0) lgkmcnt(0)
	s_barrier
	s_and_saveexec_b64 s[8:9], s[0:1]
	s_cbranch_execz .LBB0_1061
	v_mov_b32_e32 v0, 0x25fc0
	s_waitcnt vmcnt(0) lgkmcnt(0)
	ds_read_b64 v[2:3], v0
	v_readlane_b32 s3, v233, 8
	v_mov_b32_e32 v1, 1
	s_lshl_b32 s3, s3, 8
	s_add_i32 s3, s3, 0x5400
	v_mov_b32_e32 v0, s3
	global_atomic_add v4, v0, v1, s[48:49] sc0
	s_waitcnt vmcnt(0) lgkmcnt(0)
	v_readfirstlane_b32 s4, v4
	v_readfirstlane_b32 s5, v2
	v_readfirstlane_b32 s16, v3
	s_nop 3
	s_mov_b32 s17, s5
	s_mov_b32 s3, s16
